# cmp_task MFMA loop rewritten: 32 serialized load-MFMA round trips batched into double-buffered register sets (same MFMA order), s[0:1] live-out restored
# speedup vs baseline: 1.0149x; 1.0036x over previous
; #define MFMA32(a, b, c) __builtin_amdgcn_mfma_f32_32x32x16_bf16((a), (b), (c), 0, 0, 0)
; DI void cmp_task(char* ws, int layer, int q, float* ldsf, int wid, int lane, int r, int h) {
;     ...
;       const bool nok = n <= 510;
;       const bf16_t* xa_p = src + (long)(nok ? n : 0) * 2048 + wid * 512 + 8 * h;
;       const bf16_t* wb_p = wT + (long)(ct * 32 + r) * 4096 + wid * 512 + 8 * h;
; #pragma unroll 4
;       for (int ks = 0; ks < 32; ++ks) {
;         bf16x8 xa = ld8(xa_p + ks * 16), wb = ld8(wb_p + ks * 16);
;         if (!nok) {
; #pragma unroll
;           for (int j = 0; j < 8; ++j) xa[j] = 0;
;         }
;         if (which == 0) acc = MFMA32(xa, wb, acc); else acc = MFMA32(wb, xa, acc);
;       }
.LBB0_308:
	v_lshl_add_u64 v[116:117], v[42:43], 0, s[12:13]
	v_lshl_add_u64 v[118:119], v[44:45], 0, s[12:13]
	v_add_co_u32_e32 v118, vcc, 0x331dd000, v118
	s_nop 1
	v_addc_co_u32_e32 v119, vcc, 0, v119, vcc
	global_load_dwordx4 v[52:55], v[116:117], off
	global_load_dwordx4 v[68:71], v[118:119], off offset:1536
	global_load_dwordx4 v[56:59], v[116:117], off offset:32
	global_load_dwordx4 v[72:75], v[118:119], off offset:1568
	global_load_dwordx4 v[60:63], v[116:117], off offset:64
	global_load_dwordx4 v[76:79], v[118:119], off offset:1600
	global_load_dwordx4 v[64:67], v[116:117], off offset:96
	global_load_dwordx4 v[80:83], v[118:119], off offset:1632
.Lcmp_loop:
	s_add_u32 s12, s12, 0x80
	s_addc_u32 s13, s13, 0
	v_lshl_add_u64 v[116:117], v[42:43], 0, s[12:13]
	v_lshl_add_u64 v[118:119], v[44:45], 0, s[12:13]
	v_add_co_u32_e32 v118, vcc, 0x331dd000, v118
	s_nop 1
	v_addc_co_u32_e32 v119, vcc, 0, v119, vcc
	global_load_dwordx4 v[84:87], v[116:117], off
	global_load_dwordx4 v[100:103], v[118:119], off offset:1536
	global_load_dwordx4 v[88:91], v[116:117], off offset:32
	global_load_dwordx4 v[104:107], v[118:119], off offset:1568
	global_load_dwordx4 v[92:95], v[116:117], off offset:64
	global_load_dwordx4 v[108:111], v[118:119], off offset:1600
	global_load_dwordx4 v[96:99], v[116:117], off offset:96
	global_load_dwordx4 v[112:115], v[118:119], off offset:1632
	s_waitcnt vmcnt(8)
	v_cndmask_b32_e64 v18, v52, 0, s[8:9]
	v_cndmask_b32_e64 v19, v53, 0, s[8:9]
	v_cndmask_b32_e64 v20, v54, 0, s[8:9]
	v_cndmask_b32_e64 v21, v55, 0, s[8:9]
	v_cndmask_b32_e64 v38, v56, 0, s[8:9]
	v_cndmask_b32_e64 v39, v57, 0, s[8:9]
	v_cndmask_b32_e64 v40, v58, 0, s[8:9]
	v_cndmask_b32_e64 v41, v59, 0, s[8:9]
	v_cndmask_b32_e64 v120, v60, 0, s[8:9]
	v_cndmask_b32_e64 v121, v61, 0, s[8:9]
	v_cndmask_b32_e64 v122, v62, 0, s[8:9]
	v_cndmask_b32_e64 v123, v63, 0, s[8:9]
	v_cndmask_b32_e64 v124, v64, 0, s[8:9]
	v_cndmask_b32_e64 v125, v65, 0, s[8:9]
	v_cndmask_b32_e64 v126, v66, 0, s[8:9]
	v_cndmask_b32_e64 v127, v67, 0, s[8:9]
	s_and_b64 vcc, exec, s[10:11]
	s_cbranch_vccz .Lcmp_v0_1
	v_mfma_f32_32x32x16_bf16 v[2:17], v[68:71], v[18:21], v[2:17]
	v_mfma_f32_32x32x16_bf16 v[2:17], v[72:75], v[38:41], v[2:17]
	v_mfma_f32_32x32x16_bf16 v[2:17], v[76:79], v[120:123], v[2:17]
	v_mfma_f32_32x32x16_bf16 v[2:17], v[80:83], v[124:127], v[2:17]
	s_branch .Lcmp_j_1
.Lcmp_v0_1:
	v_mfma_f32_32x32x16_bf16 v[2:17], v[18:21], v[68:71], v[2:17]
	v_mfma_f32_32x32x16_bf16 v[2:17], v[38:41], v[72:75], v[2:17]
	v_mfma_f32_32x32x16_bf16 v[2:17], v[120:123], v[76:79], v[2:17]
	v_mfma_f32_32x32x16_bf16 v[2:17], v[124:127], v[80:83], v[2:17]
.Lcmp_j_1:
	s_add_u32 s12, s12, 0x80
	s_addc_u32 s13, s13, 0
	s_cmpk_eq_i32 s12, 0x400
	s_cbranch_scc1 .Lcmp_lastB
	v_lshl_add_u64 v[116:117], v[42:43], 0, s[12:13]
	v_lshl_add_u64 v[118:119], v[44:45], 0, s[12:13]
	v_add_co_u32_e32 v118, vcc, 0x331dd000, v118
	s_nop 1
	v_addc_co_u32_e32 v119, vcc, 0, v119, vcc
	global_load_dwordx4 v[52:55], v[116:117], off
	global_load_dwordx4 v[68:71], v[118:119], off offset:1536
	global_load_dwordx4 v[56:59], v[116:117], off offset:32
	global_load_dwordx4 v[72:75], v[118:119], off offset:1568
	global_load_dwordx4 v[60:63], v[116:117], off offset:64
	global_load_dwordx4 v[76:79], v[118:119], off offset:1600
	global_load_dwordx4 v[64:67], v[116:117], off offset:96
	global_load_dwordx4 v[80:83], v[118:119], off offset:1632
	s_waitcnt vmcnt(8)
	v_cndmask_b32_e64 v18, v84, 0, s[8:9]
	v_cndmask_b32_e64 v19, v85, 0, s[8:9]
	v_cndmask_b32_e64 v20, v86, 0, s[8:9]
	v_cndmask_b32_e64 v21, v87, 0, s[8:9]
	v_cndmask_b32_e64 v38, v88, 0, s[8:9]
	v_cndmask_b32_e64 v39, v89, 0, s[8:9]
	v_cndmask_b32_e64 v40, v90, 0, s[8:9]
	v_cndmask_b32_e64 v41, v91, 0, s[8:9]
	v_cndmask_b32_e64 v120, v92, 0, s[8:9]
	v_cndmask_b32_e64 v121, v93, 0, s[8:9]
	v_cndmask_b32_e64 v122, v94, 0, s[8:9]
	v_cndmask_b32_e64 v123, v95, 0, s[8:9]
	v_cndmask_b32_e64 v124, v96, 0, s[8:9]
	v_cndmask_b32_e64 v125, v97, 0, s[8:9]
	v_cndmask_b32_e64 v126, v98, 0, s[8:9]
	v_cndmask_b32_e64 v127, v99, 0, s[8:9]
	s_and_b64 vcc, exec, s[10:11]
	s_cbranch_vccz .Lcmp_v0_2
	v_mfma_f32_32x32x16_bf16 v[2:17], v[100:103], v[18:21], v[2:17]
	v_mfma_f32_32x32x16_bf16 v[2:17], v[104:107], v[38:41], v[2:17]
	v_mfma_f32_32x32x16_bf16 v[2:17], v[108:111], v[120:123], v[2:17]
	v_mfma_f32_32x32x16_bf16 v[2:17], v[112:115], v[124:127], v[2:17]
	s_branch .Lcmp_j_2
.Lcmp_v0_2:
	v_mfma_f32_32x32x16_bf16 v[2:17], v[18:21], v[100:103], v[2:17]
	v_mfma_f32_32x32x16_bf16 v[2:17], v[38:41], v[104:107], v[2:17]
	v_mfma_f32_32x32x16_bf16 v[2:17], v[120:123], v[108:111], v[2:17]
	v_mfma_f32_32x32x16_bf16 v[2:17], v[124:127], v[112:115], v[2:17]

; #define MFMA32(a, b, c) __builtin_amdgcn_mfma_f32_32x32x16_bf16((a), (b), (c), 0, 0, 0)
; DI void cmp_task(char* ws, int layer, int q, float* ldsf, int wid, int lane, int r, int h) {
;     ...
;       for (int ks = 0; ks < 32; ++ks) {
;         bf16x8 xa = ld8(xa_p + ks * 16), wb = ld8(wb_p + ks * 16);
;         if (!nok) {
; #pragma unroll
;           for (int j = 0; j < 8; ++j) xa[j] = 0;
;         }
;         if (which == 0) acc = MFMA32(xa, wb, acc); else acc = MFMA32(wb, xa, acc);
;       }
.Lcmp_lastB:
	s_waitcnt vmcnt(0)
	v_cndmask_b32_e64 v18, v84, 0, s[8:9]
	v_cndmask_b32_e64 v19, v85, 0, s[8:9]
	v_cndmask_b32_e64 v20, v86, 0, s[8:9]
	v_cndmask_b32_e64 v21, v87, 0, s[8:9]
	v_cndmask_b32_e64 v38, v88, 0, s[8:9]
	v_cndmask_b32_e64 v39, v89, 0, s[8:9]
	v_cndmask_b32_e64 v40, v90, 0, s[8:9]
	v_cndmask_b32_e64 v41, v91, 0, s[8:9]
	v_cndmask_b32_e64 v120, v92, 0, s[8:9]
	v_cndmask_b32_e64 v121, v93, 0, s[8:9]
	v_cndmask_b32_e64 v122, v94, 0, s[8:9]
	v_cndmask_b32_e64 v123, v95, 0, s[8:9]
	v_cndmask_b32_e64 v124, v96, 0, s[8:9]
	v_cndmask_b32_e64 v125, v97, 0, s[8:9]
	v_cndmask_b32_e64 v126, v98, 0, s[8:9]
	v_cndmask_b32_e64 v127, v99, 0, s[8:9]
	s_and_b64 vcc, exec, s[10:11]
	s_cbranch_vccz .Lcmp_v0_3
	v_mfma_f32_32x32x16_bf16 v[2:17], v[100:103], v[18:21], v[2:17]
	v_mfma_f32_32x32x16_bf16 v[2:17], v[104:107], v[38:41], v[2:17]
	v_mfma_f32_32x32x16_bf16 v[2:17], v[108:111], v[120:123], v[2:17]
	v_mfma_f32_32x32x16_bf16 v[2:17], v[112:115], v[124:127], v[2:17]
	s_branch .Lcmp_j_3

; #define MFMA32(a, b, c) __builtin_amdgcn_mfma_f32_32x32x16_bf16((a), (b), (c), 0, 0, 0)
; DI void cmp_task(char* ws, int layer, int q, float* ldsf, int wid, int lane, int r, int h) {
;     ...
;       for (int ks = 0; ks < 32; ++ks) {
;         bf16x8 xa = ld8(xa_p + ks * 16), wb = ld8(wb_p + ks * 16);
;         if (!nok) {
; #pragma unroll
;           for (int j = 0; j < 8; ++j) xa[j] = 0;
;         }
;         if (which == 0) acc = MFMA32(xa, wb, acc); else acc = MFMA32(wb, xa, acc);
;       }
; #pragma unroll
;       for (int i = 0; i < 16; ++i) ldsf[(wid * 16 + i) * 64 + lane] = acc[i];
.Lcmp_j_3:
	s_nop 7
	s_not_b64 s[0:1], s[10:11]
